# GEMM gate epilogue: load the two bias vectors once instead of per fragment
# speedup vs baseline: 1.0127x; 1.0033x over previous
.LBB0_251:
	s_and_b64 vcc, exec, s[50:51]
	s_cbranch_vccz .LBB0_253
	v_add_u32_e32 v150, s10, v146
	v_ashrrev_i32_e32 v151, 31, v150
	v_lshl_add_u64 v[126:127], v[150:151], 2, s[98:99]
	global_load_dwordx4 v[228:231], v[126:127], off
	global_load_dwordx4 v[232:235], v[126:127], off offset:16
	s_waitcnt vmcnt(0)
	v_mov_b32_e32 v122, v228
	v_mov_b32_e32 v123, v229
	v_mov_b32_e32 v124, v230
	v_mov_b32_e32 v125, v231
	v_mov_b32_e32 v126, v232
	v_mov_b32_e32 v127, v233
	v_mov_b32_e32 v128, v234
	v_mov_b32_e32 v129, v235
	v_add_f32_e32 v122, v176, v122
	v_add_f32_e32 v126, v188, v126
	v_add_f32_e32 v123, v177, v123
	v_add_f32_e32 v127, v189, v127
	v_add_f32_e32 v124, v172, v124
	v_add_f32_e32 v128, v186, v128
	v_add_f32_e32 v125, v173, v125
	v_add_f32_e32 v129, v187, v129
	v_mul_f32_e32 v122, 0xbfb8aa3b, v122
	v_mul_f32_e32 v126, 0xbfb8aa3b, v126
	v_mul_f32_e32 v123, 0xbfb8aa3b, v123
	v_mul_f32_e32 v127, 0xbfb8aa3b, v127
	v_mul_f32_e32 v124, 0xbfb8aa3b, v124
	v_mul_f32_e32 v128, 0xbfb8aa3b, v128
	v_mul_f32_e32 v125, 0xbfb8aa3b, v125
	v_mul_f32_e32 v129, 0xbfb8aa3b, v129
	v_exp_f32_e32 v122, v122
	v_exp_f32_e32 v126, v126
	v_exp_f32_e32 v123, v123
	v_exp_f32_e32 v127, v127
	v_exp_f32_e32 v124, v124
	v_exp_f32_e32 v128, v128
	v_exp_f32_e32 v125, v125
	v_exp_f32_e32 v129, v129
	v_add_f32_e32 v122, 1.0, v122
	v_add_f32_e32 v126, 1.0, v126
	v_add_f32_e32 v123, 1.0, v123
	v_add_f32_e32 v127, 1.0, v127
	v_add_f32_e32 v124, 1.0, v124
	v_add_f32_e32 v128, 1.0, v128
	v_add_f32_e32 v125, 1.0, v125
	v_add_f32_e32 v129, 1.0, v129
	v_rcp_f32_e32 v122, v122
	v_rcp_f32_e32 v126, v126
	v_rcp_f32_e32 v123, v123
	v_rcp_f32_e32 v127, v127
	v_rcp_f32_e32 v124, v124
	v_rcp_f32_e32 v128, v128
	v_rcp_f32_e32 v125, v125
	v_rcp_f32_e32 v129, v129
	v_mul_f32_e32 v122, 0x437f0000, v122
	v_mul_f32_e32 v126, 0x437f0000, v126
	v_mul_f32_e32 v123, 0x437f0000, v123
	v_mul_f32_e32 v127, 0x437f0000, v127
	v_mul_f32_e32 v124, 0x437f0000, v124
	v_mul_f32_e32 v128, 0x437f0000, v128
	v_mul_f32_e32 v125, 0x437f0000, v125
	v_mul_f32_e32 v129, 0x437f0000, v129
	v_rndne_f32_e32 v122, v122
	v_rndne_f32_e32 v126, v126
	v_rndne_f32_e32 v123, v123
	v_rndne_f32_e32 v127, v127
	v_rndne_f32_e32 v124, v124
	v_rndne_f32_e32 v128, v128
	v_rndne_f32_e32 v125, v125
	v_rndne_f32_e32 v129, v129
	v_cvt_u32_f32_e32 v122, v122
	v_cvt_u32_f32_e32 v126, v126
	v_cvt_u32_f32_e32 v123, v123
	v_cvt_u32_f32_e32 v127, v127
	v_cvt_u32_f32_sdwa v124, v124 dst_sel:WORD_1 dst_unused:UNUSED_PAD src0_sel:DWORD
	v_cvt_u32_f32_sdwa v128, v128 dst_sel:WORD_1 dst_unused:UNUSED_PAD src0_sel:DWORD
	v_cvt_u32_f32_sdwa v125, v125 dst_sel:BYTE_3 dst_unused:UNUSED_PAD src0_sel:DWORD
	v_cvt_u32_f32_sdwa v129, v129 dst_sel:BYTE_3 dst_unused:UNUSED_PAD src0_sel:DWORD
	v_lshl_or_b32 v122, v123, 8, v122
	v_lshl_or_b32 v123, v127, 8, v126
	v_or3_b32 v122, v122, v124, v125
	v_or3_b32 v123, v123, v128, v129
	v_lshl_add_u64 v[124:125], v[162:163], 0, v[150:151]
	global_store_dwordx2 v[124:125], v[122:123], off

.LBB0_308:
	s_and_b64 vcc, exec, s[50:51]
	s_cbranch_vccz .LBB0_310
	v_add_u32_e32 v168, s10, v122
	v_ashrrev_i32_e32 v169, 31, v168
	v_lshl_add_u64 v[118:119], v[168:169], 2, s[98:99]
	global_load_dwordx4 v[236:239], v[118:119], off
	global_load_dwordx2 v[240:241], v[118:119], off offset:16
	global_load_dwordx2 v[206:207], v[118:119], off offset:24
	s_waitcnt vmcnt(0)
	v_mov_b32_e32 v114, v236
	v_mov_b32_e32 v115, v237
	v_mov_b32_e32 v116, v238
	v_mov_b32_e32 v117, v239
	v_mov_b32_e32 v118, v240
	v_mov_b32_e32 v119, v241
	v_mov_b32_e32 v120, v206
	v_mov_b32_e32 v121, v207
	v_add_f32_e32 v114, v172, v114
	v_add_f32_e32 v118, v178, v118
	v_add_f32_e32 v115, v173, v115
	v_add_f32_e32 v119, v179, v119
	v_add_f32_e32 v116, v124, v116
	v_add_f32_e32 v120, v176, v120
	v_add_f32_e32 v117, v125, v117
	v_add_f32_e32 v121, v177, v121
	v_mul_f32_e32 v114, 0xbfb8aa3b, v114
	v_mul_f32_e32 v118, 0xbfb8aa3b, v118
	v_mul_f32_e32 v115, 0xbfb8aa3b, v115
	v_mul_f32_e32 v119, 0xbfb8aa3b, v119
	v_mul_f32_e32 v116, 0xbfb8aa3b, v116
	v_mul_f32_e32 v120, 0xbfb8aa3b, v120
	v_mul_f32_e32 v117, 0xbfb8aa3b, v117
	v_mul_f32_e32 v121, 0xbfb8aa3b, v121
	v_exp_f32_e32 v114, v114
	v_exp_f32_e32 v118, v118
	v_exp_f32_e32 v115, v115
	v_exp_f32_e32 v119, v119
	v_exp_f32_e32 v116, v116
	v_exp_f32_e32 v120, v120
	v_exp_f32_e32 v117, v117
	v_exp_f32_e32 v121, v121
	v_add_f32_e32 v114, 1.0, v114
	v_add_f32_e32 v118, 1.0, v118
	v_add_f32_e32 v115, 1.0, v115
	v_add_f32_e32 v119, 1.0, v119
	v_add_f32_e32 v116, 1.0, v116
	v_add_f32_e32 v120, 1.0, v120
	v_add_f32_e32 v117, 1.0, v117
	v_add_f32_e32 v121, 1.0, v121
	v_rcp_f32_e32 v114, v114
	v_rcp_f32_e32 v118, v118
	v_rcp_f32_e32 v115, v115
	v_rcp_f32_e32 v119, v119
	v_rcp_f32_e32 v116, v116
	v_rcp_f32_e32 v120, v120
	v_rcp_f32_e32 v117, v117
	v_rcp_f32_e32 v121, v121
	v_mul_f32_e32 v114, 0x437f0000, v114
	v_mul_f32_e32 v118, 0x437f0000, v118
	v_mul_f32_e32 v115, 0x437f0000, v115
	v_mul_f32_e32 v119, 0x437f0000, v119
	v_mul_f32_e32 v116, 0x437f0000, v116
	v_mul_f32_e32 v120, 0x437f0000, v120
	v_mul_f32_e32 v117, 0x437f0000, v117
	v_mul_f32_e32 v121, 0x437f0000, v121
	v_rndne_f32_e32 v114, v114
	v_rndne_f32_e32 v118, v118
	v_rndne_f32_e32 v115, v115
	v_rndne_f32_e32 v119, v119
	v_rndne_f32_e32 v116, v116
	v_rndne_f32_e32 v120, v120
	v_rndne_f32_e32 v117, v117
	v_rndne_f32_e32 v121, v121
	v_cvt_u32_f32_e32 v114, v114
	v_cvt_u32_f32_e32 v118, v118
	v_cvt_u32_f32_e32 v115, v115
	v_cvt_u32_f32_e32 v119, v119
	v_cvt_u32_f32_sdwa v116, v116 dst_sel:WORD_1 dst_unused:UNUSED_PAD src0_sel:DWORD
	v_cvt_u32_f32_sdwa v120, v120 dst_sel:WORD_1 dst_unused:UNUSED_PAD src0_sel:DWORD
	v_cvt_u32_f32_sdwa v117, v117 dst_sel:BYTE_3 dst_unused:UNUSED_PAD src0_sel:DWORD
	v_cvt_u32_f32_sdwa v121, v121 dst_sel:BYTE_3 dst_unused:UNUSED_PAD src0_sel:DWORD
	v_lshl_or_b32 v114, v115, 8, v114
	v_lshl_or_b32 v115, v119, 8, v118
	v_or3_b32 v114, v114, v116, v117
	v_or3_b32 v115, v115, v120, v121
	v_lshl_add_u64 v[116:117], v[162:163], 0, v[168:169]
	global_store_dwordx2 v[116:117], v[114:115], off

.LBB0_381:
	s_and_b64 vcc, exec, s[50:51]
	s_cbranch_vccz .LBB0_383
	v_add_u32_e32 v120, s10, v146
	v_ashrrev_i32_e32 v121, 31, v120
	v_mov_b32_e32 v106, v228
	v_mov_b32_e32 v107, v229
	v_mov_b32_e32 v108, v230
	v_mov_b32_e32 v109, v231
	v_mov_b32_e32 v110, v232
	v_mov_b32_e32 v111, v233
	v_mov_b32_e32 v112, v234
	v_mov_b32_e32 v113, v235
	v_add_f32_e32 v106, v174, v106
	v_add_f32_e32 v110, v178, v110
	v_add_f32_e32 v107, v175, v107
	v_add_f32_e32 v111, v179, v111
	v_add_f32_e32 v108, v162, v108
	v_add_f32_e32 v112, v176, v112
	v_add_f32_e32 v109, v163, v109
	v_add_f32_e32 v113, v177, v113
	v_mul_f32_e32 v106, 0xbfb8aa3b, v106
	v_mul_f32_e32 v110, 0xbfb8aa3b, v110
	v_mul_f32_e32 v107, 0xbfb8aa3b, v107
	v_mul_f32_e32 v111, 0xbfb8aa3b, v111
	v_mul_f32_e32 v108, 0xbfb8aa3b, v108
	v_mul_f32_e32 v112, 0xbfb8aa3b, v112
	v_mul_f32_e32 v109, 0xbfb8aa3b, v109
	v_mul_f32_e32 v113, 0xbfb8aa3b, v113
	v_exp_f32_e32 v106, v106
	v_exp_f32_e32 v110, v110
	v_exp_f32_e32 v107, v107
	v_exp_f32_e32 v111, v111
	v_exp_f32_e32 v108, v108
	v_exp_f32_e32 v112, v112
	v_exp_f32_e32 v109, v109
	v_exp_f32_e32 v113, v113
	v_add_f32_e32 v106, 1.0, v106
	v_add_f32_e32 v110, 1.0, v110
	v_add_f32_e32 v107, 1.0, v107
	v_add_f32_e32 v111, 1.0, v111
	v_add_f32_e32 v108, 1.0, v108
	v_add_f32_e32 v112, 1.0, v112
	v_add_f32_e32 v109, 1.0, v109
	v_add_f32_e32 v113, 1.0, v113
	v_rcp_f32_e32 v106, v106
	v_rcp_f32_e32 v110, v110
	v_rcp_f32_e32 v107, v107
	v_rcp_f32_e32 v111, v111
	v_rcp_f32_e32 v108, v108
	v_rcp_f32_e32 v112, v112
	v_rcp_f32_e32 v109, v109
	v_rcp_f32_e32 v113, v113
	v_mul_f32_e32 v106, 0x437f0000, v106
	v_mul_f32_e32 v110, 0x437f0000, v110
	v_mul_f32_e32 v107, 0x437f0000, v107
	v_mul_f32_e32 v111, 0x437f0000, v111
	v_mul_f32_e32 v108, 0x437f0000, v108
	v_mul_f32_e32 v112, 0x437f0000, v112
	v_mul_f32_e32 v109, 0x437f0000, v109
	v_mul_f32_e32 v113, 0x437f0000, v113
	v_rndne_f32_e32 v106, v106
	v_rndne_f32_e32 v110, v110
	v_rndne_f32_e32 v107, v107
	v_rndne_f32_e32 v111, v111
	v_rndne_f32_e32 v108, v108
	v_rndne_f32_e32 v112, v112
	v_rndne_f32_e32 v109, v109
	v_rndne_f32_e32 v113, v113
	v_cvt_u32_f32_e32 v106, v106
	v_cvt_u32_f32_e32 v110, v110
	v_cvt_u32_f32_e32 v107, v107
	v_cvt_u32_f32_e32 v111, v111
	v_cvt_u32_f32_sdwa v108, v108 dst_sel:WORD_1 dst_unused:UNUSED_PAD src0_sel:DWORD
	v_cvt_u32_f32_sdwa v112, v112 dst_sel:WORD_1 dst_unused:UNUSED_PAD src0_sel:DWORD
	v_cvt_u32_f32_sdwa v109, v109 dst_sel:BYTE_3 dst_unused:UNUSED_PAD src0_sel:DWORD
	v_cvt_u32_f32_sdwa v113, v113 dst_sel:BYTE_3 dst_unused:UNUSED_PAD src0_sel:DWORD
	v_lshl_or_b32 v106, v107, 8, v106
	v_lshl_or_b32 v107, v111, 8, v110
	v_or3_b32 v106, v106, v108, v109
	v_or3_b32 v107, v107, v112, v113
	v_lshl_add_u64 v[108:109], v[152:153], 0, v[120:121]
	global_store_dwordx2 v[108:109], v[106:107], off

.LBB0_440:
	s_and_b64 vcc, exec, s[50:51]
	s_cbranch_vccz .LBB0_442
	v_add_u32_e32 v158, s10, v122
	v_ashrrev_i32_e32 v159, 31, v158
	v_mov_b32_e32 v98, v236
	v_mov_b32_e32 v99, v237
	v_mov_b32_e32 v100, v238
	v_mov_b32_e32 v101, v239
	v_mov_b32_e32 v102, v240
	v_mov_b32_e32 v103, v241
	v_mov_b32_e32 v104, v206
	v_mov_b32_e32 v105, v207
	v_add_f32_e32 v98, v108, v98
	v_add_f32_e32 v102, v164, v102
	v_add_f32_e32 v99, v109, v99
	v_add_f32_e32 v103, v165, v103
	v_add_f32_e32 v100, v106, v100
	v_add_f32_e32 v104, v162, v104
	v_add_f32_e32 v101, v107, v101
	v_add_f32_e32 v105, v163, v105
	v_mul_f32_e32 v98, 0xbfb8aa3b, v98
	v_mul_f32_e32 v102, 0xbfb8aa3b, v102
	v_mul_f32_e32 v99, 0xbfb8aa3b, v99
	v_mul_f32_e32 v103, 0xbfb8aa3b, v103
	v_mul_f32_e32 v100, 0xbfb8aa3b, v100
	v_mul_f32_e32 v104, 0xbfb8aa3b, v104
	v_mul_f32_e32 v101, 0xbfb8aa3b, v101
	v_mul_f32_e32 v105, 0xbfb8aa3b, v105
	v_exp_f32_e32 v98, v98
	v_exp_f32_e32 v102, v102
	v_exp_f32_e32 v99, v99
	v_exp_f32_e32 v103, v103
	v_exp_f32_e32 v100, v100
	v_exp_f32_e32 v104, v104
	v_exp_f32_e32 v101, v101
	v_exp_f32_e32 v105, v105
	v_add_f32_e32 v98, 1.0, v98
	v_add_f32_e32 v102, 1.0, v102
	v_add_f32_e32 v99, 1.0, v99
	v_add_f32_e32 v103, 1.0, v103
	v_add_f32_e32 v100, 1.0, v100
	v_add_f32_e32 v104, 1.0, v104
	v_add_f32_e32 v101, 1.0, v101
	v_add_f32_e32 v105, 1.0, v105
	v_rcp_f32_e32 v98, v98
	v_rcp_f32_e32 v102, v102
	v_rcp_f32_e32 v99, v99
	v_rcp_f32_e32 v103, v103
	v_rcp_f32_e32 v100, v100
	v_rcp_f32_e32 v104, v104
	v_rcp_f32_e32 v101, v101
	v_rcp_f32_e32 v105, v105
	v_mul_f32_e32 v98, 0x437f0000, v98
	v_mul_f32_e32 v102, 0x437f0000, v102
	v_mul_f32_e32 v99, 0x437f0000, v99
	v_mul_f32_e32 v103, 0x437f0000, v103
	v_mul_f32_e32 v100, 0x437f0000, v100
	v_mul_f32_e32 v104, 0x437f0000, v104
	v_mul_f32_e32 v101, 0x437f0000, v101
	v_mul_f32_e32 v105, 0x437f0000, v105
	v_rndne_f32_e32 v98, v98
	v_rndne_f32_e32 v102, v102
	v_rndne_f32_e32 v99, v99
	v_rndne_f32_e32 v103, v103
	v_rndne_f32_e32 v100, v100
	v_rndne_f32_e32 v104, v104
	v_rndne_f32_e32 v101, v101
	v_rndne_f32_e32 v105, v105
	v_cvt_u32_f32_e32 v98, v98
	v_cvt_u32_f32_e32 v102, v102
	v_cvt_u32_f32_e32 v99, v99
	v_cvt_u32_f32_e32 v103, v103
	v_cvt_u32_f32_sdwa v100, v100 dst_sel:WORD_1 dst_unused:UNUSED_PAD src0_sel:DWORD
	v_cvt_u32_f32_sdwa v104, v104 dst_sel:WORD_1 dst_unused:UNUSED_PAD src0_sel:DWORD
	v_cvt_u32_f32_sdwa v101, v101 dst_sel:BYTE_3 dst_unused:UNUSED_PAD src0_sel:DWORD
	v_cvt_u32_f32_sdwa v105, v105 dst_sel:BYTE_3 dst_unused:UNUSED_PAD src0_sel:DWORD
	v_lshl_or_b32 v98, v99, 8, v98
	v_lshl_or_b32 v99, v103, 8, v102
	v_or3_b32 v98, v98, v100, v101
	v_or3_b32 v99, v99, v104, v105
	v_lshl_add_u64 v[100:101], v[152:153], 0, v[158:159]
	global_store_dwordx2 v[100:101], v[98:99], off

.LBB0_508:
	s_and_b64 vcc, exec, s[50:51]
	s_cbranch_vccz .LBB0_510
	v_add_u32_e32 v102, s10, v146
	v_ashrrev_i32_e32 v103, 31, v102
	v_mov_b32_e32 v90, v228
	v_mov_b32_e32 v91, v229
	v_mov_b32_e32 v92, v230
	v_mov_b32_e32 v93, v231
	v_mov_b32_e32 v94, v232
	v_mov_b32_e32 v95, v233
	v_mov_b32_e32 v96, v234
	v_mov_b32_e32 v97, v235
	v_add_f32_e32 v90, v158, v90
	v_add_f32_e32 v94, v162, v94
	v_add_f32_e32 v91, v159, v91
	v_add_f32_e32 v95, v163, v95
	v_add_f32_e32 v92, v120, v92
	v_add_f32_e32 v96, v160, v96
	v_add_f32_e32 v93, v121, v93
	v_add_f32_e32 v97, v161, v97
	v_mul_f32_e32 v90, 0xbfb8aa3b, v90
	v_mul_f32_e32 v94, 0xbfb8aa3b, v94
	v_mul_f32_e32 v91, 0xbfb8aa3b, v91
	v_mul_f32_e32 v95, 0xbfb8aa3b, v95
	v_mul_f32_e32 v92, 0xbfb8aa3b, v92
	v_mul_f32_e32 v96, 0xbfb8aa3b, v96
	v_mul_f32_e32 v93, 0xbfb8aa3b, v93
	v_mul_f32_e32 v97, 0xbfb8aa3b, v97
	v_exp_f32_e32 v90, v90
	v_exp_f32_e32 v94, v94
	v_exp_f32_e32 v91, v91
	v_exp_f32_e32 v95, v95
	v_exp_f32_e32 v92, v92
	v_exp_f32_e32 v96, v96
	v_exp_f32_e32 v93, v93
	v_exp_f32_e32 v97, v97
	v_add_f32_e32 v90, 1.0, v90
	v_add_f32_e32 v94, 1.0, v94
	v_add_f32_e32 v91, 1.0, v91
	v_add_f32_e32 v95, 1.0, v95
	v_add_f32_e32 v92, 1.0, v92
	v_add_f32_e32 v96, 1.0, v96
	v_add_f32_e32 v93, 1.0, v93
	v_add_f32_e32 v97, 1.0, v97
	v_rcp_f32_e32 v90, v90
	v_rcp_f32_e32 v94, v94
	v_rcp_f32_e32 v91, v91
	v_rcp_f32_e32 v95, v95
	v_rcp_f32_e32 v92, v92
	v_rcp_f32_e32 v96, v96
	v_rcp_f32_e32 v93, v93
	v_rcp_f32_e32 v97, v97
	v_mul_f32_e32 v90, 0x437f0000, v90
	v_mul_f32_e32 v94, 0x437f0000, v94
	v_mul_f32_e32 v91, 0x437f0000, v91
	v_mul_f32_e32 v95, 0x437f0000, v95
	v_mul_f32_e32 v92, 0x437f0000, v92
	v_mul_f32_e32 v96, 0x437f0000, v96
	v_mul_f32_e32 v93, 0x437f0000, v93
	v_mul_f32_e32 v97, 0x437f0000, v97
	v_rndne_f32_e32 v90, v90
	v_rndne_f32_e32 v94, v94
	v_rndne_f32_e32 v91, v91
	v_rndne_f32_e32 v95, v95
	v_rndne_f32_e32 v92, v92
	v_rndne_f32_e32 v96, v96
	v_rndne_f32_e32 v93, v93
	v_rndne_f32_e32 v97, v97
	v_cvt_u32_f32_e32 v90, v90
	v_cvt_u32_f32_e32 v94, v94
	v_cvt_u32_f32_e32 v91, v91
	v_cvt_u32_f32_e32 v95, v95
	v_cvt_u32_f32_sdwa v92, v92 dst_sel:WORD_1 dst_unused:UNUSED_PAD src0_sel:DWORD
	v_cvt_u32_f32_sdwa v96, v96 dst_sel:WORD_1 dst_unused:UNUSED_PAD src0_sel:DWORD
	v_cvt_u32_f32_sdwa v93, v93 dst_sel:BYTE_3 dst_unused:UNUSED_PAD src0_sel:DWORD
	v_cvt_u32_f32_sdwa v97, v97 dst_sel:BYTE_3 dst_unused:UNUSED_PAD src0_sel:DWORD
	v_lshl_or_b32 v90, v91, 8, v90
	v_lshl_or_b32 v91, v95, 8, v94
	v_or3_b32 v90, v90, v92, v93
	v_or3_b32 v91, v91, v96, v97
	v_lshl_add_u64 v[92:93], v[108:109], 0, v[102:103]
	global_store_dwordx2 v[92:93], v[90:91], off

.LBB0_570:
	s_and_b64 vcc, exec, s[50:51]
	s_cbranch_vccz .LBB0_572
	v_add_u32_e32 v116, s10, v122
	v_ashrrev_i32_e32 v117, 31, v116
	v_mov_b32_e32 v82, v236
	v_mov_b32_e32 v83, v237
	v_mov_b32_e32 v84, v238
	v_mov_b32_e32 v85, v239
	v_mov_b32_e32 v86, v240
	v_mov_b32_e32 v87, v241
	v_mov_b32_e32 v88, v206
	v_mov_b32_e32 v89, v207
	v_add_f32_e32 v82, v92, v82
	v_add_f32_e32 v86, v124, v86
	v_add_f32_e32 v83, v93, v83
	v_add_f32_e32 v87, v125, v87
	v_add_f32_e32 v84, v90, v84
	v_add_f32_e32 v88, v120, v88
	v_add_f32_e32 v85, v91, v85
	v_add_f32_e32 v89, v121, v89
	v_mul_f32_e32 v82, 0xbfb8aa3b, v82
	v_mul_f32_e32 v86, 0xbfb8aa3b, v86
	v_mul_f32_e32 v83, 0xbfb8aa3b, v83
	v_mul_f32_e32 v87, 0xbfb8aa3b, v87
	v_mul_f32_e32 v84, 0xbfb8aa3b, v84
	v_mul_f32_e32 v88, 0xbfb8aa3b, v88
	v_mul_f32_e32 v85, 0xbfb8aa3b, v85
	v_mul_f32_e32 v89, 0xbfb8aa3b, v89
	v_exp_f32_e32 v82, v82
	v_exp_f32_e32 v86, v86
	v_exp_f32_e32 v83, v83
	v_exp_f32_e32 v87, v87
	v_exp_f32_e32 v84, v84
	v_exp_f32_e32 v88, v88
	v_exp_f32_e32 v85, v85
	v_exp_f32_e32 v89, v89
	v_add_f32_e32 v82, 1.0, v82
	v_add_f32_e32 v86, 1.0, v86
	v_add_f32_e32 v83, 1.0, v83
	v_add_f32_e32 v87, 1.0, v87
	v_add_f32_e32 v84, 1.0, v84
	v_add_f32_e32 v88, 1.0, v88
	v_add_f32_e32 v85, 1.0, v85
	v_add_f32_e32 v89, 1.0, v89
	v_rcp_f32_e32 v82, v82
	v_rcp_f32_e32 v86, v86
	v_rcp_f32_e32 v83, v83
	v_rcp_f32_e32 v87, v87
	v_rcp_f32_e32 v84, v84
	v_rcp_f32_e32 v88, v88
	v_rcp_f32_e32 v85, v85
	v_rcp_f32_e32 v89, v89
	v_mul_f32_e32 v82, 0x437f0000, v82
	v_mul_f32_e32 v86, 0x437f0000, v86
	v_mul_f32_e32 v83, 0x437f0000, v83
	v_mul_f32_e32 v87, 0x437f0000, v87
	v_mul_f32_e32 v84, 0x437f0000, v84
	v_mul_f32_e32 v88, 0x437f0000, v88
	v_mul_f32_e32 v85, 0x437f0000, v85
	v_mul_f32_e32 v89, 0x437f0000, v89
	v_rndne_f32_e32 v82, v82
	v_rndne_f32_e32 v86, v86
	v_rndne_f32_e32 v83, v83
	v_rndne_f32_e32 v87, v87
	v_rndne_f32_e32 v84, v84
	v_rndne_f32_e32 v88, v88
	v_rndne_f32_e32 v85, v85
	v_rndne_f32_e32 v89, v89
	v_cvt_u32_f32_e32 v82, v82
	v_cvt_u32_f32_e32 v86, v86
	v_cvt_u32_f32_e32 v83, v83
	v_cvt_u32_f32_e32 v87, v87
	v_cvt_u32_f32_sdwa v84, v84 dst_sel:WORD_1 dst_unused:UNUSED_PAD src0_sel:DWORD
	v_cvt_u32_f32_sdwa v88, v88 dst_sel:WORD_1 dst_unused:UNUSED_PAD src0_sel:DWORD
	v_cvt_u32_f32_sdwa v85, v85 dst_sel:BYTE_3 dst_unused:UNUSED_PAD src0_sel:DWORD
	v_cvt_u32_f32_sdwa v89, v89 dst_sel:BYTE_3 dst_unused:UNUSED_PAD src0_sel:DWORD
	v_lshl_or_b32 v82, v83, 8, v82
	v_lshl_or_b32 v83, v87, 8, v86
	v_or3_b32 v82, v82, v84, v85
	v_or3_b32 v83, v83, v88, v89
	v_lshl_add_u64 v[84:85], v[108:109], 0, v[116:117]
	global_store_dwordx2 v[84:85], v[82:83], off

.LBB0_638:
	s_and_b64 vcc, exec, s[50:51]
	s_cbranch_vccz .LBB0_640
	v_add_u32_e32 v86, s10, v146
	v_ashrrev_i32_e32 v87, 31, v86
	v_mov_b32_e32 v74, v228
	v_mov_b32_e32 v75, v229
	v_mov_b32_e32 v76, v230
	v_mov_b32_e32 v77, v231
	v_mov_b32_e32 v78, v232
	v_mov_b32_e32 v79, v233
	v_mov_b32_e32 v80, v234
	v_mov_b32_e32 v81, v235
	v_add_f32_e32 v74, v116, v74
	v_add_f32_e32 v78, v120, v78
	v_add_f32_e32 v75, v117, v75
	v_add_f32_e32 v79, v121, v79
	v_add_f32_e32 v76, v102, v76
	v_add_f32_e32 v80, v118, v80
	v_add_f32_e32 v77, v103, v77
	v_add_f32_e32 v81, v119, v81
	v_mul_f32_e32 v74, 0xbfb8aa3b, v74
	v_mul_f32_e32 v78, 0xbfb8aa3b, v78
	v_mul_f32_e32 v75, 0xbfb8aa3b, v75
	v_mul_f32_e32 v79, 0xbfb8aa3b, v79
	v_mul_f32_e32 v76, 0xbfb8aa3b, v76
	v_mul_f32_e32 v80, 0xbfb8aa3b, v80
	v_mul_f32_e32 v77, 0xbfb8aa3b, v77
	v_mul_f32_e32 v81, 0xbfb8aa3b, v81
	v_exp_f32_e32 v74, v74
	v_exp_f32_e32 v78, v78
	v_exp_f32_e32 v75, v75
	v_exp_f32_e32 v79, v79
	v_exp_f32_e32 v76, v76
	v_exp_f32_e32 v80, v80
	v_exp_f32_e32 v77, v77
	v_exp_f32_e32 v81, v81
	v_add_f32_e32 v74, 1.0, v74
	v_add_f32_e32 v78, 1.0, v78
	v_add_f32_e32 v75, 1.0, v75
	v_add_f32_e32 v79, 1.0, v79
	v_add_f32_e32 v76, 1.0, v76
	v_add_f32_e32 v80, 1.0, v80
	v_add_f32_e32 v77, 1.0, v77
	v_add_f32_e32 v81, 1.0, v81
	v_rcp_f32_e32 v74, v74
	v_rcp_f32_e32 v78, v78
	v_rcp_f32_e32 v75, v75
	v_rcp_f32_e32 v79, v79
	v_rcp_f32_e32 v76, v76
	v_rcp_f32_e32 v80, v80
	v_rcp_f32_e32 v77, v77
	v_rcp_f32_e32 v81, v81
	v_mul_f32_e32 v74, 0x437f0000, v74
	v_mul_f32_e32 v78, 0x437f0000, v78
	v_mul_f32_e32 v75, 0x437f0000, v75
	v_mul_f32_e32 v79, 0x437f0000, v79
	v_mul_f32_e32 v76, 0x437f0000, v76
	v_mul_f32_e32 v80, 0x437f0000, v80
	v_mul_f32_e32 v77, 0x437f0000, v77
	v_mul_f32_e32 v81, 0x437f0000, v81
	v_rndne_f32_e32 v74, v74
	v_rndne_f32_e32 v78, v78
	v_rndne_f32_e32 v75, v75
	v_rndne_f32_e32 v79, v79
	v_rndne_f32_e32 v76, v76
	v_rndne_f32_e32 v80, v80
	v_rndne_f32_e32 v77, v77
	v_rndne_f32_e32 v81, v81
	v_cvt_u32_f32_e32 v74, v74
	v_cvt_u32_f32_e32 v78, v78
	v_cvt_u32_f32_e32 v75, v75
	v_cvt_u32_f32_e32 v79, v79
	v_cvt_u32_f32_sdwa v76, v76 dst_sel:WORD_1 dst_unused:UNUSED_PAD src0_sel:DWORD
	v_cvt_u32_f32_sdwa v80, v80 dst_sel:WORD_1 dst_unused:UNUSED_PAD src0_sel:DWORD
	v_cvt_u32_f32_sdwa v77, v77 dst_sel:BYTE_3 dst_unused:UNUSED_PAD src0_sel:DWORD
	v_cvt_u32_f32_sdwa v81, v81 dst_sel:BYTE_3 dst_unused:UNUSED_PAD src0_sel:DWORD
	v_lshl_or_b32 v74, v75, 8, v74
	v_lshl_or_b32 v75, v79, 8, v78
	v_or3_b32 v74, v74, v76, v77
	v_or3_b32 v75, v75, v80, v81
	v_lshl_add_u64 v[76:77], v[92:93], 0, v[86:87]
	global_store_dwordx2 v[76:77], v[74:75], off

.LBB0_700:
	s_and_b64 vcc, exec, s[50:51]
	s_cbranch_vccz .LBB0_702
	v_add_u32_e32 v98, s10, v122
	v_ashrrev_i32_e32 v99, 31, v98
	v_mov_b32_e32 v66, v236
	v_mov_b32_e32 v67, v237
	v_mov_b32_e32 v68, v238
	v_mov_b32_e32 v69, v239
	v_mov_b32_e32 v70, v240
	v_mov_b32_e32 v71, v241
	v_mov_b32_e32 v72, v206
	v_mov_b32_e32 v73, v207
	v_add_f32_e32 v66, v76, v66
	v_add_f32_e32 v70, v104, v70
	v_add_f32_e32 v67, v77, v67
	v_add_f32_e32 v71, v105, v71
	v_add_f32_e32 v68, v74, v68
	v_add_f32_e32 v72, v102, v72
	v_add_f32_e32 v69, v75, v69
	v_add_f32_e32 v73, v103, v73
	v_mul_f32_e32 v66, 0xbfb8aa3b, v66
	v_mul_f32_e32 v70, 0xbfb8aa3b, v70
	v_mul_f32_e32 v67, 0xbfb8aa3b, v67
	v_mul_f32_e32 v71, 0xbfb8aa3b, v71
	v_mul_f32_e32 v68, 0xbfb8aa3b, v68
	v_mul_f32_e32 v72, 0xbfb8aa3b, v72
	v_mul_f32_e32 v69, 0xbfb8aa3b, v69
	v_mul_f32_e32 v73, 0xbfb8aa3b, v73
	v_exp_f32_e32 v66, v66
	v_exp_f32_e32 v70, v70
	v_exp_f32_e32 v67, v67
	v_exp_f32_e32 v71, v71
	v_exp_f32_e32 v68, v68
	v_exp_f32_e32 v72, v72
	v_exp_f32_e32 v69, v69
	v_exp_f32_e32 v73, v73
	v_add_f32_e32 v66, 1.0, v66
	v_add_f32_e32 v70, 1.0, v70
	v_add_f32_e32 v67, 1.0, v67
	v_add_f32_e32 v71, 1.0, v71
	v_add_f32_e32 v68, 1.0, v68
	v_add_f32_e32 v72, 1.0, v72
	v_add_f32_e32 v69, 1.0, v69
	v_add_f32_e32 v73, 1.0, v73
	v_rcp_f32_e32 v66, v66
	v_rcp_f32_e32 v70, v70
	v_rcp_f32_e32 v67, v67
	v_rcp_f32_e32 v71, v71
	v_rcp_f32_e32 v68, v68
	v_rcp_f32_e32 v72, v72
	v_rcp_f32_e32 v69, v69
	v_rcp_f32_e32 v73, v73
	v_mul_f32_e32 v66, 0x437f0000, v66
	v_mul_f32_e32 v70, 0x437f0000, v70
	v_mul_f32_e32 v67, 0x437f0000, v67
	v_mul_f32_e32 v71, 0x437f0000, v71
	v_mul_f32_e32 v68, 0x437f0000, v68
	v_mul_f32_e32 v72, 0x437f0000, v72
	v_mul_f32_e32 v69, 0x437f0000, v69
	v_mul_f32_e32 v73, 0x437f0000, v73
	v_rndne_f32_e32 v66, v66
	v_rndne_f32_e32 v70, v70
	v_rndne_f32_e32 v67, v67
	v_rndne_f32_e32 v71, v71
	v_rndne_f32_e32 v68, v68
	v_rndne_f32_e32 v72, v72
	v_rndne_f32_e32 v69, v69
	v_rndne_f32_e32 v73, v73
	v_cvt_u32_f32_e32 v66, v66
	v_cvt_u32_f32_e32 v70, v70
	v_cvt_u32_f32_e32 v67, v67
	v_cvt_u32_f32_e32 v71, v71
	v_cvt_u32_f32_sdwa v68, v68 dst_sel:WORD_1 dst_unused:UNUSED_PAD src0_sel:DWORD
	v_cvt_u32_f32_sdwa v72, v72 dst_sel:WORD_1 dst_unused:UNUSED_PAD src0_sel:DWORD
	v_cvt_u32_f32_sdwa v69, v69 dst_sel:BYTE_3 dst_unused:UNUSED_PAD src0_sel:DWORD
	v_cvt_u32_f32_sdwa v73, v73 dst_sel:BYTE_3 dst_unused:UNUSED_PAD src0_sel:DWORD
	v_lshl_or_b32 v66, v67, 8, v66
	v_lshl_or_b32 v67, v71, 8, v70
	v_or3_b32 v66, v66, v68, v69
	v_or3_b32 v67, v67, v72, v73
	v_lshl_add_u64 v[68:69], v[92:93], 0, v[98:99]
	global_store_dwordx2 v[68:69], v[66:67], off

.LBB0_768:
	s_and_b64 vcc, exec, s[50:51]
	s_cbranch_vccz .LBB0_770
	v_add_u32_e32 v70, s10, v146
	v_ashrrev_i32_e32 v71, 31, v70
	v_mov_b32_e32 v58, v228
	v_mov_b32_e32 v59, v229
	v_mov_b32_e32 v60, v230
	v_mov_b32_e32 v61, v231
	v_mov_b32_e32 v62, v232
	v_mov_b32_e32 v63, v233
	v_mov_b32_e32 v64, v234
	v_mov_b32_e32 v65, v235
	v_add_f32_e32 v58, v98, v58
	v_add_f32_e32 v62, v102, v62
	v_add_f32_e32 v59, v99, v59
	v_add_f32_e32 v63, v103, v63
	v_add_f32_e32 v60, v86, v60
	v_add_f32_e32 v64, v100, v64
	v_add_f32_e32 v61, v87, v61
	v_add_f32_e32 v65, v101, v65
	v_mul_f32_e32 v58, 0xbfb8aa3b, v58
	v_mul_f32_e32 v62, 0xbfb8aa3b, v62
	v_mul_f32_e32 v59, 0xbfb8aa3b, v59
	v_mul_f32_e32 v63, 0xbfb8aa3b, v63
	v_mul_f32_e32 v60, 0xbfb8aa3b, v60
	v_mul_f32_e32 v64, 0xbfb8aa3b, v64
	v_mul_f32_e32 v61, 0xbfb8aa3b, v61
	v_mul_f32_e32 v65, 0xbfb8aa3b, v65
	v_exp_f32_e32 v58, v58
	v_exp_f32_e32 v62, v62
	v_exp_f32_e32 v59, v59
	v_exp_f32_e32 v63, v63
	v_exp_f32_e32 v60, v60
	v_exp_f32_e32 v64, v64
	v_exp_f32_e32 v61, v61
	v_exp_f32_e32 v65, v65
	v_add_f32_e32 v58, 1.0, v58
	v_add_f32_e32 v62, 1.0, v62
	v_add_f32_e32 v59, 1.0, v59
	v_add_f32_e32 v63, 1.0, v63
	v_add_f32_e32 v60, 1.0, v60
	v_add_f32_e32 v64, 1.0, v64
	v_add_f32_e32 v61, 1.0, v61
	v_add_f32_e32 v65, 1.0, v65
	v_rcp_f32_e32 v58, v58
	v_rcp_f32_e32 v62, v62
	v_rcp_f32_e32 v59, v59
	v_rcp_f32_e32 v63, v63
	v_rcp_f32_e32 v60, v60
	v_rcp_f32_e32 v64, v64
	v_rcp_f32_e32 v61, v61
	v_rcp_f32_e32 v65, v65
	v_mul_f32_e32 v58, 0x437f0000, v58
	v_mul_f32_e32 v62, 0x437f0000, v62
	v_mul_f32_e32 v59, 0x437f0000, v59
	v_mul_f32_e32 v63, 0x437f0000, v63
	v_mul_f32_e32 v60, 0x437f0000, v60
	v_mul_f32_e32 v64, 0x437f0000, v64
	v_mul_f32_e32 v61, 0x437f0000, v61
	v_mul_f32_e32 v65, 0x437f0000, v65
	v_rndne_f32_e32 v58, v58
	v_rndne_f32_e32 v62, v62
	v_rndne_f32_e32 v59, v59
	v_rndne_f32_e32 v63, v63
	v_rndne_f32_e32 v60, v60
	v_rndne_f32_e32 v64, v64
	v_rndne_f32_e32 v61, v61
	v_rndne_f32_e32 v65, v65
	v_cvt_u32_f32_e32 v58, v58
	v_cvt_u32_f32_e32 v62, v62
	v_cvt_u32_f32_e32 v59, v59
	v_cvt_u32_f32_e32 v63, v63
	v_cvt_u32_f32_sdwa v60, v60 dst_sel:WORD_1 dst_unused:UNUSED_PAD src0_sel:DWORD
	v_cvt_u32_f32_sdwa v64, v64 dst_sel:WORD_1 dst_unused:UNUSED_PAD src0_sel:DWORD
	v_cvt_u32_f32_sdwa v61, v61 dst_sel:BYTE_3 dst_unused:UNUSED_PAD src0_sel:DWORD
	v_cvt_u32_f32_sdwa v65, v65 dst_sel:BYTE_3 dst_unused:UNUSED_PAD src0_sel:DWORD
	v_lshl_or_b32 v58, v59, 8, v58
	v_lshl_or_b32 v59, v63, 8, v62
	v_or3_b32 v58, v58, v60, v61
	v_or3_b32 v59, v59, v64, v65
	v_lshl_add_u64 v[60:61], v[76:77], 0, v[70:71]
	global_store_dwordx2 v[60:61], v[58:59], off

.LBB0_830:
	s_and_b64 vcc, exec, s[50:51]
	s_cbranch_vccz .LBB0_832
	v_add_u32_e32 v82, s10, v122
	v_ashrrev_i32_e32 v83, 31, v82
	v_mov_b32_e32 v50, v236
	v_mov_b32_e32 v51, v237
	v_mov_b32_e32 v52, v238
	v_mov_b32_e32 v53, v239
	v_mov_b32_e32 v54, v240
	v_mov_b32_e32 v55, v241
	v_mov_b32_e32 v56, v206
	v_mov_b32_e32 v57, v207
	v_add_f32_e32 v50, v60, v50
	v_add_f32_e32 v54, v88, v54
	v_add_f32_e32 v51, v61, v51
	v_add_f32_e32 v55, v89, v55
	v_add_f32_e32 v52, v58, v52
	v_add_f32_e32 v56, v86, v56
	v_add_f32_e32 v53, v59, v53
	v_add_f32_e32 v57, v87, v57
	v_mul_f32_e32 v50, 0xbfb8aa3b, v50
	v_mul_f32_e32 v54, 0xbfb8aa3b, v54
	v_mul_f32_e32 v51, 0xbfb8aa3b, v51
	v_mul_f32_e32 v55, 0xbfb8aa3b, v55
	v_mul_f32_e32 v52, 0xbfb8aa3b, v52
	v_mul_f32_e32 v56, 0xbfb8aa3b, v56
	v_mul_f32_e32 v53, 0xbfb8aa3b, v53
	v_mul_f32_e32 v57, 0xbfb8aa3b, v57
	v_exp_f32_e32 v50, v50
	v_exp_f32_e32 v54, v54
	v_exp_f32_e32 v51, v51
	v_exp_f32_e32 v55, v55
	v_exp_f32_e32 v52, v52
	v_exp_f32_e32 v56, v56
	v_exp_f32_e32 v53, v53
	v_exp_f32_e32 v57, v57
	v_add_f32_e32 v50, 1.0, v50
	v_add_f32_e32 v54, 1.0, v54
	v_add_f32_e32 v51, 1.0, v51
	v_add_f32_e32 v55, 1.0, v55
	v_add_f32_e32 v52, 1.0, v52
	v_add_f32_e32 v56, 1.0, v56
	v_add_f32_e32 v53, 1.0, v53
	v_add_f32_e32 v57, 1.0, v57
	v_rcp_f32_e32 v50, v50
	v_rcp_f32_e32 v54, v54
	v_rcp_f32_e32 v51, v51
	v_rcp_f32_e32 v55, v55
	v_rcp_f32_e32 v52, v52
	v_rcp_f32_e32 v56, v56
	v_rcp_f32_e32 v53, v53
	v_rcp_f32_e32 v57, v57
	v_mul_f32_e32 v50, 0x437f0000, v50
	v_mul_f32_e32 v54, 0x437f0000, v54
	v_mul_f32_e32 v51, 0x437f0000, v51
	v_mul_f32_e32 v55, 0x437f0000, v55
	v_mul_f32_e32 v52, 0x437f0000, v52
	v_mul_f32_e32 v56, 0x437f0000, v56
	v_mul_f32_e32 v53, 0x437f0000, v53
	v_mul_f32_e32 v57, 0x437f0000, v57
	v_rndne_f32_e32 v50, v50
	v_rndne_f32_e32 v54, v54
	v_rndne_f32_e32 v51, v51
	v_rndne_f32_e32 v55, v55
	v_rndne_f32_e32 v52, v52
	v_rndne_f32_e32 v56, v56
	v_rndne_f32_e32 v53, v53
	v_rndne_f32_e32 v57, v57
	v_cvt_u32_f32_e32 v50, v50
	v_cvt_u32_f32_e32 v54, v54
	v_cvt_u32_f32_e32 v51, v51
	v_cvt_u32_f32_e32 v55, v55
	v_cvt_u32_f32_sdwa v52, v52 dst_sel:WORD_1 dst_unused:UNUSED_PAD src0_sel:DWORD
	v_cvt_u32_f32_sdwa v56, v56 dst_sel:WORD_1 dst_unused:UNUSED_PAD src0_sel:DWORD
	v_cvt_u32_f32_sdwa v53, v53 dst_sel:BYTE_3 dst_unused:UNUSED_PAD src0_sel:DWORD
	v_cvt_u32_f32_sdwa v57, v57 dst_sel:BYTE_3 dst_unused:UNUSED_PAD src0_sel:DWORD
	v_lshl_or_b32 v50, v51, 8, v50
	v_lshl_or_b32 v51, v55, 8, v54
	v_or3_b32 v50, v50, v52, v53
	v_or3_b32 v51, v51, v56, v57
	v_lshl_add_u64 v[52:53], v[76:77], 0, v[82:83]
	global_store_dwordx2 v[52:53], v[50:51], off

.LBB0_898:
	s_and_b64 vcc, exec, s[50:51]
	s_cbranch_vccz .LBB0_900
	v_add_u32_e32 v54, s10, v146
	v_ashrrev_i32_e32 v55, 31, v54
	v_mov_b32_e32 v42, v228
	v_mov_b32_e32 v43, v229
	v_mov_b32_e32 v44, v230
	v_mov_b32_e32 v45, v231
	v_mov_b32_e32 v46, v232
	v_mov_b32_e32 v47, v233
	v_mov_b32_e32 v48, v234
	v_mov_b32_e32 v49, v235
	v_add_f32_e32 v42, v82, v42
	v_add_f32_e32 v46, v86, v46
	v_add_f32_e32 v43, v83, v43
	v_add_f32_e32 v47, v87, v47
	v_add_f32_e32 v44, v70, v44
	v_add_f32_e32 v48, v84, v48
	v_add_f32_e32 v45, v71, v45
	v_add_f32_e32 v49, v85, v49
	v_mul_f32_e32 v42, 0xbfb8aa3b, v42
	v_mul_f32_e32 v46, 0xbfb8aa3b, v46
	v_mul_f32_e32 v43, 0xbfb8aa3b, v43
	v_mul_f32_e32 v47, 0xbfb8aa3b, v47
	v_mul_f32_e32 v44, 0xbfb8aa3b, v44
	v_mul_f32_e32 v48, 0xbfb8aa3b, v48
	v_mul_f32_e32 v45, 0xbfb8aa3b, v45
	v_mul_f32_e32 v49, 0xbfb8aa3b, v49
	v_exp_f32_e32 v42, v42
	v_exp_f32_e32 v46, v46
	v_exp_f32_e32 v43, v43
	v_exp_f32_e32 v47, v47
	v_exp_f32_e32 v44, v44
	v_exp_f32_e32 v48, v48
	v_exp_f32_e32 v45, v45
	v_exp_f32_e32 v49, v49
	v_add_f32_e32 v42, 1.0, v42
	v_add_f32_e32 v46, 1.0, v46
	v_add_f32_e32 v43, 1.0, v43
	v_add_f32_e32 v47, 1.0, v47
	v_add_f32_e32 v44, 1.0, v44
	v_add_f32_e32 v48, 1.0, v48
	v_add_f32_e32 v45, 1.0, v45
	v_add_f32_e32 v49, 1.0, v49
	v_rcp_f32_e32 v42, v42
	v_rcp_f32_e32 v46, v46
	v_rcp_f32_e32 v43, v43
	v_rcp_f32_e32 v47, v47
	v_rcp_f32_e32 v44, v44
	v_rcp_f32_e32 v48, v48
	v_rcp_f32_e32 v45, v45
	v_rcp_f32_e32 v49, v49
	v_mul_f32_e32 v42, 0x437f0000, v42
	v_mul_f32_e32 v46, 0x437f0000, v46
	v_mul_f32_e32 v43, 0x437f0000, v43
	v_mul_f32_e32 v47, 0x437f0000, v47
	v_mul_f32_e32 v44, 0x437f0000, v44
	v_mul_f32_e32 v48, 0x437f0000, v48
	v_mul_f32_e32 v45, 0x437f0000, v45
	v_mul_f32_e32 v49, 0x437f0000, v49
	v_rndne_f32_e32 v42, v42
	v_rndne_f32_e32 v46, v46
	v_rndne_f32_e32 v43, v43
	v_rndne_f32_e32 v47, v47
	v_rndne_f32_e32 v44, v44
	v_rndne_f32_e32 v48, v48
	v_rndne_f32_e32 v45, v45
	v_rndne_f32_e32 v49, v49
	v_cvt_u32_f32_e32 v42, v42
	v_cvt_u32_f32_e32 v46, v46
	v_cvt_u32_f32_e32 v43, v43
	v_cvt_u32_f32_e32 v47, v47
	v_cvt_u32_f32_sdwa v44, v44 dst_sel:WORD_1 dst_unused:UNUSED_PAD src0_sel:DWORD
	v_cvt_u32_f32_sdwa v48, v48 dst_sel:WORD_1 dst_unused:UNUSED_PAD src0_sel:DWORD
	v_cvt_u32_f32_sdwa v45, v45 dst_sel:BYTE_3 dst_unused:UNUSED_PAD src0_sel:DWORD
	v_cvt_u32_f32_sdwa v49, v49 dst_sel:BYTE_3 dst_unused:UNUSED_PAD src0_sel:DWORD
	v_lshl_or_b32 v42, v43, 8, v42
	v_lshl_or_b32 v43, v47, 8, v46
	v_or3_b32 v42, v42, v44, v45
	v_or3_b32 v43, v43, v48, v49
	v_lshl_add_u64 v[44:45], v[60:61], 0, v[54:55]
	global_store_dwordx2 v[44:45], v[42:43], off

.LBB0_960:
	s_and_b64 vcc, exec, s[50:51]
	s_cbranch_vccz .LBB0_962
	v_add_u32_e32 v66, s10, v122
	v_ashrrev_i32_e32 v67, 31, v66
	v_mov_b32_e32 v34, v236
	v_mov_b32_e32 v35, v237
	v_mov_b32_e32 v36, v238
	v_mov_b32_e32 v37, v239
	v_mov_b32_e32 v38, v240
	v_mov_b32_e32 v39, v241
	v_mov_b32_e32 v40, v206
	v_mov_b32_e32 v41, v207
	v_add_f32_e32 v34, v44, v34
	v_add_f32_e32 v38, v72, v38
	v_add_f32_e32 v35, v45, v35
	v_add_f32_e32 v39, v73, v39
	v_add_f32_e32 v36, v42, v36
	v_add_f32_e32 v40, v70, v40
	v_add_f32_e32 v37, v43, v37
	v_add_f32_e32 v41, v71, v41
	v_mul_f32_e32 v34, 0xbfb8aa3b, v34
	v_mul_f32_e32 v38, 0xbfb8aa3b, v38
	v_mul_f32_e32 v35, 0xbfb8aa3b, v35
	v_mul_f32_e32 v39, 0xbfb8aa3b, v39
	v_mul_f32_e32 v36, 0xbfb8aa3b, v36
	v_mul_f32_e32 v40, 0xbfb8aa3b, v40
	v_mul_f32_e32 v37, 0xbfb8aa3b, v37
	v_mul_f32_e32 v41, 0xbfb8aa3b, v41
	v_exp_f32_e32 v34, v34
	v_exp_f32_e32 v38, v38
	v_exp_f32_e32 v35, v35
	v_exp_f32_e32 v39, v39
	v_exp_f32_e32 v36, v36
	v_exp_f32_e32 v40, v40
	v_exp_f32_e32 v37, v37
	v_exp_f32_e32 v41, v41
	v_add_f32_e32 v34, 1.0, v34
	v_add_f32_e32 v38, 1.0, v38
	v_add_f32_e32 v35, 1.0, v35
	v_add_f32_e32 v39, 1.0, v39
	v_add_f32_e32 v36, 1.0, v36
	v_add_f32_e32 v40, 1.0, v40
	v_add_f32_e32 v37, 1.0, v37
	v_add_f32_e32 v41, 1.0, v41
	v_rcp_f32_e32 v34, v34
	v_rcp_f32_e32 v38, v38
	v_rcp_f32_e32 v35, v35
	v_rcp_f32_e32 v39, v39
	v_rcp_f32_e32 v36, v36
	v_rcp_f32_e32 v40, v40
	v_rcp_f32_e32 v37, v37
	v_rcp_f32_e32 v41, v41
	v_mul_f32_e32 v34, 0x437f0000, v34
	v_mul_f32_e32 v38, 0x437f0000, v38
	v_mul_f32_e32 v35, 0x437f0000, v35
	v_mul_f32_e32 v39, 0x437f0000, v39
	v_mul_f32_e32 v36, 0x437f0000, v36
	v_mul_f32_e32 v40, 0x437f0000, v40
	v_mul_f32_e32 v37, 0x437f0000, v37
	v_mul_f32_e32 v41, 0x437f0000, v41
	v_rndne_f32_e32 v34, v34
	v_rndne_f32_e32 v38, v38
	v_rndne_f32_e32 v35, v35
	v_rndne_f32_e32 v39, v39
	v_rndne_f32_e32 v36, v36
	v_rndne_f32_e32 v40, v40
	v_rndne_f32_e32 v37, v37
	v_rndne_f32_e32 v41, v41
	v_cvt_u32_f32_e32 v34, v34
	v_cvt_u32_f32_e32 v38, v38
	v_cvt_u32_f32_e32 v35, v35
	v_cvt_u32_f32_e32 v39, v39
	v_cvt_u32_f32_sdwa v36, v36 dst_sel:WORD_1 dst_unused:UNUSED_PAD src0_sel:DWORD
	v_cvt_u32_f32_sdwa v40, v40 dst_sel:WORD_1 dst_unused:UNUSED_PAD src0_sel:DWORD
	v_cvt_u32_f32_sdwa v37, v37 dst_sel:BYTE_3 dst_unused:UNUSED_PAD src0_sel:DWORD
	v_cvt_u32_f32_sdwa v41, v41 dst_sel:BYTE_3 dst_unused:UNUSED_PAD src0_sel:DWORD
	v_lshl_or_b32 v34, v35, 8, v34
	v_lshl_or_b32 v35, v39, 8, v38
	v_or3_b32 v34, v34, v36, v37
	v_or3_b32 v35, v35, v40, v41
	v_lshl_add_u64 v[36:37], v[60:61], 0, v[66:67]
	global_store_dwordx2 v[36:37], v[34:35], off

.LBB0_1028:
	s_and_b64 vcc, exec, s[50:51]
	s_cbranch_vccz .LBB0_1030
	v_add_u32_e32 v38, s10, v146
	v_ashrrev_i32_e32 v39, 31, v38
	v_mov_b32_e32 v26, v228
	v_mov_b32_e32 v27, v229
	v_mov_b32_e32 v28, v230
	v_mov_b32_e32 v29, v231
	v_mov_b32_e32 v30, v232
	v_mov_b32_e32 v31, v233
	v_mov_b32_e32 v32, v234
	v_mov_b32_e32 v33, v235
	v_add_f32_e32 v26, v66, v26
	v_add_f32_e32 v30, v70, v30
	v_add_f32_e32 v27, v67, v27
	v_add_f32_e32 v31, v71, v31
	v_add_f32_e32 v28, v54, v28
	v_add_f32_e32 v32, v68, v32
	v_add_f32_e32 v29, v55, v29
	v_add_f32_e32 v33, v69, v33
	v_mul_f32_e32 v26, 0xbfb8aa3b, v26
	v_mul_f32_e32 v30, 0xbfb8aa3b, v30
	v_mul_f32_e32 v27, 0xbfb8aa3b, v27
	v_mul_f32_e32 v31, 0xbfb8aa3b, v31
	v_mul_f32_e32 v28, 0xbfb8aa3b, v28
	v_mul_f32_e32 v32, 0xbfb8aa3b, v32
	v_mul_f32_e32 v29, 0xbfb8aa3b, v29
	v_mul_f32_e32 v33, 0xbfb8aa3b, v33
	v_exp_f32_e32 v26, v26
	v_exp_f32_e32 v30, v30
	v_exp_f32_e32 v27, v27
	v_exp_f32_e32 v31, v31
	v_exp_f32_e32 v28, v28
	v_exp_f32_e32 v32, v32
	v_exp_f32_e32 v29, v29
	v_exp_f32_e32 v33, v33
	v_add_f32_e32 v26, 1.0, v26
	v_add_f32_e32 v30, 1.0, v30
	v_add_f32_e32 v27, 1.0, v27
	v_add_f32_e32 v31, 1.0, v31
	v_add_f32_e32 v28, 1.0, v28
	v_add_f32_e32 v32, 1.0, v32
	v_add_f32_e32 v29, 1.0, v29
	v_add_f32_e32 v33, 1.0, v33
	v_rcp_f32_e32 v26, v26
	v_rcp_f32_e32 v30, v30
	v_rcp_f32_e32 v27, v27
	v_rcp_f32_e32 v31, v31
	v_rcp_f32_e32 v28, v28
	v_rcp_f32_e32 v32, v32
	v_rcp_f32_e32 v29, v29
	v_rcp_f32_e32 v33, v33
	v_mul_f32_e32 v26, 0x437f0000, v26
	v_mul_f32_e32 v30, 0x437f0000, v30
	v_mul_f32_e32 v27, 0x437f0000, v27
	v_mul_f32_e32 v31, 0x437f0000, v31
	v_mul_f32_e32 v28, 0x437f0000, v28
	v_mul_f32_e32 v32, 0x437f0000, v32
	v_mul_f32_e32 v29, 0x437f0000, v29
	v_mul_f32_e32 v33, 0x437f0000, v33
	v_rndne_f32_e32 v26, v26
	v_rndne_f32_e32 v30, v30
	v_rndne_f32_e32 v27, v27
	v_rndne_f32_e32 v31, v31
	v_rndne_f32_e32 v28, v28
	v_rndne_f32_e32 v32, v32
	v_rndne_f32_e32 v29, v29
	v_rndne_f32_e32 v33, v33
	v_cvt_u32_f32_e32 v26, v26
	v_cvt_u32_f32_e32 v30, v30
	v_cvt_u32_f32_e32 v27, v27
	v_cvt_u32_f32_e32 v31, v31
	v_cvt_u32_f32_sdwa v28, v28 dst_sel:WORD_1 dst_unused:UNUSED_PAD src0_sel:DWORD
	v_cvt_u32_f32_sdwa v32, v32 dst_sel:WORD_1 dst_unused:UNUSED_PAD src0_sel:DWORD
	v_cvt_u32_f32_sdwa v29, v29 dst_sel:BYTE_3 dst_unused:UNUSED_PAD src0_sel:DWORD
	v_cvt_u32_f32_sdwa v33, v33 dst_sel:BYTE_3 dst_unused:UNUSED_PAD src0_sel:DWORD
	v_lshl_or_b32 v26, v27, 8, v26
	v_lshl_or_b32 v27, v31, 8, v30
	v_or3_b32 v26, v26, v28, v29
	v_or3_b32 v27, v27, v32, v33
	v_lshl_add_u64 v[28:29], v[44:45], 0, v[38:39]
	global_store_dwordx2 v[28:29], v[26:27], off

.LBB0_1090:
	s_and_b64 vcc, exec, s[50:51]
	s_cbranch_vccz .LBB0_1092
	v_add_u32_e32 v50, s10, v122
	v_ashrrev_i32_e32 v51, 31, v50
	v_mov_b32_e32 v18, v236
	v_mov_b32_e32 v19, v237
	v_mov_b32_e32 v20, v238
	v_mov_b32_e32 v21, v239
	v_mov_b32_e32 v22, v240
	v_mov_b32_e32 v23, v241
	v_mov_b32_e32 v24, v206
	v_mov_b32_e32 v25, v207
	v_add_f32_e32 v18, v28, v18
	v_add_f32_e32 v22, v56, v22
	v_add_f32_e32 v19, v29, v19
	v_add_f32_e32 v23, v57, v23
	v_add_f32_e32 v20, v26, v20
	v_add_f32_e32 v24, v54, v24
	v_add_f32_e32 v21, v27, v21
	v_add_f32_e32 v25, v55, v25
	v_mul_f32_e32 v18, 0xbfb8aa3b, v18
	v_mul_f32_e32 v22, 0xbfb8aa3b, v22
	v_mul_f32_e32 v19, 0xbfb8aa3b, v19
	v_mul_f32_e32 v23, 0xbfb8aa3b, v23
	v_mul_f32_e32 v20, 0xbfb8aa3b, v20
	v_mul_f32_e32 v24, 0xbfb8aa3b, v24
	v_mul_f32_e32 v21, 0xbfb8aa3b, v21
	v_mul_f32_e32 v25, 0xbfb8aa3b, v25
	v_exp_f32_e32 v18, v18
	v_exp_f32_e32 v22, v22
	v_exp_f32_e32 v19, v19
	v_exp_f32_e32 v23, v23
	v_exp_f32_e32 v20, v20
	v_exp_f32_e32 v24, v24
	v_exp_f32_e32 v21, v21
	v_exp_f32_e32 v25, v25
	v_add_f32_e32 v18, 1.0, v18
	v_add_f32_e32 v22, 1.0, v22
	v_add_f32_e32 v19, 1.0, v19
	v_add_f32_e32 v23, 1.0, v23
	v_add_f32_e32 v20, 1.0, v20
	v_add_f32_e32 v24, 1.0, v24
	v_add_f32_e32 v21, 1.0, v21
	v_add_f32_e32 v25, 1.0, v25
	v_rcp_f32_e32 v18, v18
	v_rcp_f32_e32 v22, v22
	v_rcp_f32_e32 v19, v19
	v_rcp_f32_e32 v23, v23
	v_rcp_f32_e32 v20, v20
	v_rcp_f32_e32 v24, v24
	v_rcp_f32_e32 v21, v21
	v_rcp_f32_e32 v25, v25
	v_mul_f32_e32 v18, 0x437f0000, v18
	v_mul_f32_e32 v22, 0x437f0000, v22
	v_mul_f32_e32 v19, 0x437f0000, v19
	v_mul_f32_e32 v23, 0x437f0000, v23
	v_mul_f32_e32 v20, 0x437f0000, v20
	v_mul_f32_e32 v24, 0x437f0000, v24
	v_mul_f32_e32 v21, 0x437f0000, v21
	v_mul_f32_e32 v25, 0x437f0000, v25
	v_rndne_f32_e32 v18, v18
	v_rndne_f32_e32 v22, v22
	v_rndne_f32_e32 v19, v19
	v_rndne_f32_e32 v23, v23
	v_rndne_f32_e32 v20, v20
	v_rndne_f32_e32 v24, v24
	v_rndne_f32_e32 v21, v21
	v_rndne_f32_e32 v25, v25
	v_cvt_u32_f32_e32 v18, v18
	v_cvt_u32_f32_e32 v22, v22
	v_cvt_u32_f32_e32 v19, v19
	v_cvt_u32_f32_e32 v23, v23
	v_cvt_u32_f32_sdwa v20, v20 dst_sel:WORD_1 dst_unused:UNUSED_PAD src0_sel:DWORD
	v_cvt_u32_f32_sdwa v24, v24 dst_sel:WORD_1 dst_unused:UNUSED_PAD src0_sel:DWORD
	v_cvt_u32_f32_sdwa v21, v21 dst_sel:BYTE_3 dst_unused:UNUSED_PAD src0_sel:DWORD
	v_cvt_u32_f32_sdwa v25, v25 dst_sel:BYTE_3 dst_unused:UNUSED_PAD src0_sel:DWORD
	v_lshl_or_b32 v18, v19, 8, v18
	v_lshl_or_b32 v19, v23, 8, v22
	v_or3_b32 v18, v18, v20, v21
	v_or3_b32 v19, v19, v24, v25
	v_lshl_add_u64 v[20:21], v[44:45], 0, v[50:51]
	global_store_dwordx2 v[20:21], v[18:19], off

.LBB0_1158:
	s_and_b64 vcc, exec, s[28:29]
	s_cbranch_vccz .LBB0_1160
	v_add_u32_e32 v22, s10, v146
	v_ashrrev_i32_e32 v23, 31, v22
	v_mov_b32_e32 v10, v228
	v_mov_b32_e32 v11, v229
	v_mov_b32_e32 v12, v230
	v_mov_b32_e32 v13, v231
	v_mov_b32_e32 v14, v232
	v_mov_b32_e32 v15, v233
	v_mov_b32_e32 v16, v234
	v_mov_b32_e32 v17, v235
	v_add_f32_e32 v10, v50, v10
	v_add_f32_e32 v14, v54, v14
	v_add_f32_e32 v11, v51, v11
	v_add_f32_e32 v15, v55, v15
	v_add_f32_e32 v12, v38, v12
	v_add_f32_e32 v16, v52, v16
	v_add_f32_e32 v13, v39, v13
	v_add_f32_e32 v17, v53, v17
	v_mul_f32_e32 v10, 0xbfb8aa3b, v10
	v_mul_f32_e32 v14, 0xbfb8aa3b, v14
	v_mul_f32_e32 v11, 0xbfb8aa3b, v11
	v_mul_f32_e32 v15, 0xbfb8aa3b, v15
	v_mul_f32_e32 v12, 0xbfb8aa3b, v12
	v_mul_f32_e32 v16, 0xbfb8aa3b, v16
	v_mul_f32_e32 v13, 0xbfb8aa3b, v13
	v_mul_f32_e32 v17, 0xbfb8aa3b, v17
	v_exp_f32_e32 v10, v10
	v_exp_f32_e32 v14, v14
	v_exp_f32_e32 v11, v11
	v_exp_f32_e32 v15, v15
	v_exp_f32_e32 v12, v12
	v_exp_f32_e32 v16, v16
	v_exp_f32_e32 v13, v13
	v_exp_f32_e32 v17, v17
	v_add_f32_e32 v10, 1.0, v10
	v_add_f32_e32 v14, 1.0, v14
	v_add_f32_e32 v11, 1.0, v11
	v_add_f32_e32 v15, 1.0, v15
	v_add_f32_e32 v12, 1.0, v12
	v_add_f32_e32 v16, 1.0, v16
	v_add_f32_e32 v13, 1.0, v13
	v_add_f32_e32 v17, 1.0, v17
	v_rcp_f32_e32 v10, v10
	v_rcp_f32_e32 v14, v14
	v_rcp_f32_e32 v11, v11
	v_rcp_f32_e32 v15, v15
	v_rcp_f32_e32 v12, v12
	v_rcp_f32_e32 v16, v16
	v_rcp_f32_e32 v13, v13
	v_rcp_f32_e32 v17, v17
	v_mul_f32_e32 v10, 0x437f0000, v10
	v_mul_f32_e32 v14, 0x437f0000, v14
	v_mul_f32_e32 v11, 0x437f0000, v11
	v_mul_f32_e32 v15, 0x437f0000, v15
	v_mul_f32_e32 v12, 0x437f0000, v12
	v_mul_f32_e32 v16, 0x437f0000, v16
	v_mul_f32_e32 v13, 0x437f0000, v13
	v_mul_f32_e32 v17, 0x437f0000, v17
	v_rndne_f32_e32 v10, v10
	v_rndne_f32_e32 v14, v14
	v_rndne_f32_e32 v11, v11
	v_rndne_f32_e32 v15, v15
	v_rndne_f32_e32 v12, v12
	v_rndne_f32_e32 v16, v16
	v_rndne_f32_e32 v13, v13
	v_rndne_f32_e32 v17, v17
	v_cvt_u32_f32_e32 v10, v10
	v_cvt_u32_f32_e32 v14, v14
	v_cvt_u32_f32_e32 v11, v11
	v_cvt_u32_f32_e32 v15, v15
	v_cvt_u32_f32_sdwa v12, v12 dst_sel:WORD_1 dst_unused:UNUSED_PAD src0_sel:DWORD
	v_cvt_u32_f32_sdwa v16, v16 dst_sel:WORD_1 dst_unused:UNUSED_PAD src0_sel:DWORD
	v_cvt_u32_f32_sdwa v13, v13 dst_sel:BYTE_3 dst_unused:UNUSED_PAD src0_sel:DWORD
	v_cvt_u32_f32_sdwa v17, v17 dst_sel:BYTE_3 dst_unused:UNUSED_PAD src0_sel:DWORD
	v_lshl_or_b32 v10, v11, 8, v10
	v_lshl_or_b32 v11, v15, 8, v14
	v_or3_b32 v10, v10, v12, v13
	v_or3_b32 v11, v11, v16, v17
	v_lshl_add_u64 v[12:13], v[28:29], 0, v[22:23]
	global_store_dwordx2 v[12:13], v[10:11], off

.LBB0_1221:
	s_and_b64 vcc, exec, s[20:21]
	s_cbranch_vccz .LBB0_1223
	v_add_u32_e32 v34, s10, v122
	v_ashrrev_i32_e32 v35, 31, v34
	v_mov_b32_e32 v2, v236
	v_mov_b32_e32 v3, v237
	v_mov_b32_e32 v4, v238
	v_mov_b32_e32 v5, v239
	v_mov_b32_e32 v6, v240
	v_mov_b32_e32 v7, v241
	v_mov_b32_e32 v8, v206
	v_mov_b32_e32 v9, v207
	v_add_f32_e32 v2, v12, v2
	v_add_f32_e32 v6, v40, v6
	v_add_f32_e32 v3, v13, v3
	v_add_f32_e32 v7, v41, v7
	v_add_f32_e32 v4, v10, v4
	v_add_f32_e32 v8, v38, v8
	v_add_f32_e32 v5, v11, v5
	v_add_f32_e32 v9, v39, v9
	v_mul_f32_e32 v2, 0xbfb8aa3b, v2
	v_mul_f32_e32 v6, 0xbfb8aa3b, v6
	v_mul_f32_e32 v3, 0xbfb8aa3b, v3
	v_mul_f32_e32 v7, 0xbfb8aa3b, v7
	v_mul_f32_e32 v4, 0xbfb8aa3b, v4
	v_mul_f32_e32 v8, 0xbfb8aa3b, v8
	v_mul_f32_e32 v5, 0xbfb8aa3b, v5
	v_mul_f32_e32 v9, 0xbfb8aa3b, v9
	v_exp_f32_e32 v2, v2
	v_exp_f32_e32 v6, v6
	v_exp_f32_e32 v3, v3
	v_exp_f32_e32 v7, v7
	v_exp_f32_e32 v4, v4
	v_exp_f32_e32 v8, v8
	v_exp_f32_e32 v5, v5
	v_exp_f32_e32 v9, v9
	v_add_f32_e32 v2, 1.0, v2
	v_add_f32_e32 v6, 1.0, v6
	v_add_f32_e32 v3, 1.0, v3
	v_add_f32_e32 v7, 1.0, v7
	v_add_f32_e32 v4, 1.0, v4
	v_add_f32_e32 v8, 1.0, v8
	v_add_f32_e32 v5, 1.0, v5
	v_add_f32_e32 v9, 1.0, v9
	v_rcp_f32_e32 v2, v2
	v_rcp_f32_e32 v6, v6
	v_rcp_f32_e32 v3, v3
	v_rcp_f32_e32 v7, v7
	v_rcp_f32_e32 v4, v4
	v_rcp_f32_e32 v8, v8
	v_rcp_f32_e32 v5, v5
	v_rcp_f32_e32 v9, v9
	v_mul_f32_e32 v2, 0x437f0000, v2
	v_mul_f32_e32 v6, 0x437f0000, v6
	v_mul_f32_e32 v3, 0x437f0000, v3
	v_mul_f32_e32 v7, 0x437f0000, v7
	v_mul_f32_e32 v4, 0x437f0000, v4
	v_mul_f32_e32 v8, 0x437f0000, v8
	v_mul_f32_e32 v5, 0x437f0000, v5
	v_mul_f32_e32 v9, 0x437f0000, v9
	v_rndne_f32_e32 v2, v2
	v_rndne_f32_e32 v6, v6
	v_rndne_f32_e32 v3, v3
	v_rndne_f32_e32 v7, v7
	v_rndne_f32_e32 v4, v4
	v_rndne_f32_e32 v8, v8
	v_rndne_f32_e32 v5, v5
	v_rndne_f32_e32 v9, v9
	v_cvt_u32_f32_e32 v2, v2
	v_cvt_u32_f32_e32 v6, v6
	v_cvt_u32_f32_e32 v3, v3
	v_cvt_u32_f32_e32 v7, v7
	v_cvt_u32_f32_sdwa v4, v4 dst_sel:WORD_1 dst_unused:UNUSED_PAD src0_sel:DWORD
	v_cvt_u32_f32_sdwa v8, v8 dst_sel:WORD_1 dst_unused:UNUSED_PAD src0_sel:DWORD
	v_cvt_u32_f32_sdwa v5, v5 dst_sel:BYTE_3 dst_unused:UNUSED_PAD src0_sel:DWORD
	v_cvt_u32_f32_sdwa v9, v9 dst_sel:BYTE_3 dst_unused:UNUSED_PAD src0_sel:DWORD
	v_lshl_or_b32 v2, v3, 8, v2
	v_lshl_or_b32 v3, v7, 8, v6
	v_or3_b32 v2, v2, v4, v5
	v_or3_b32 v3, v3, v8, v9
	v_lshl_add_u64 v[4:5], v[28:29], 0, v[34:35]
	global_store_dwordx2 v[4:5], v[2:3], off
